# PROJ GEMM epilogue hand-written: destination buffer (projA/projG/projZ) selected once per tile with scalar base + per-lane offsets instead of a per-store branch chain re-reading 16 spilled SGPRs; f32
# speedup vs baseline: 1.0155x; 1.0079x over previous
.LBB0_211:
	s_or_b64 exec, exec, s[0:1]
	v_readlane_b32 s2, v254, 41
	v_readlane_b32 s3, v254, 42
	v_readlane_b32 s0, v253, 0
	s_mov_b32 s3, s97
	s_waitcnt lgkmcnt(0)
	s_barrier
	s_ashr_i32 s8, s0, 3
	v_writelane_b32 v254, s2, 41
	s_cmpk_gt_i32 s8, 0x197
	s_nop 0
	v_writelane_b32 v254, s3, 42
	s_cbranch_scc1 .LBB0_351
	v_readlane_b32 s12, v253, 36
	v_readlane_b32 s13, v253, 37
	v_readlane_b32 s14, v253, 38
	v_readlane_b32 s15, v253, 39
	v_readlane_b32 s16, v253, 40
	v_readlane_b32 s17, v253, 41
	v_readlane_b32 s18, v253, 42
	v_readlane_b32 s19, v253, 43
	v_readlane_b32 s20, v253, 44
	v_readlane_b32 s21, v253, 45
	v_readlane_b32 s2, v254, 41
	v_readlane_b32 s22, v253, 46
	v_readlane_b32 s23, v253, 47
	v_readlane_b32 s24, v253, 48
	v_readlane_b32 s25, v253, 49
	v_readlane_b32 s26, v253, 50
	v_readlane_b32 s27, v253, 51
	s_mov_b64 s[12:13], s[20:21]
	s_mul_i32 s1, s2, 0x600000
	s_mov_b64 s[16:17], s[24:25]
	s_add_u32 s9, s16, s1
	s_addc_u32 s10, s17, 0
	s_and_b32 s11, s0, 7
	s_mul_i32 s11, s11, 17
	v_readlane_b32 s3, v254, 42
	s_mov_b64 s[14:15], s[22:23]
	s_mov_b64 s[18:19], s[26:27]
	s_mov_b32 s100, 0
	s_branch .LBB0_215

.Lg16_proj_k:
	s_add_i32 s3, s1, 2
	s_lshl_b32 s96, s3, 13
	s_add_i32 m0, vcc_lo, 16384
	v_lshl_add_u64 v[160:161], v[188:189], 0, s[96:97]
	global_load_lds_dwordx4 v[160:161], off
	global_load_lds_dwordx4 v[160:161], off offset:1024
	ds_read_b128 v[236:239], v196 offset:0
	ds_read_b128 v[240:243], v196 offset:1024
	ds_read_b128 v[244:247], v196 offset:2048
	ds_read_b128 v[248:251], v196 offset:3072
	s_add_i32 s3, s1, 2
	s_lshl_b32 s96, s3, 11
	v_lshl_add_u64 v[198:199], v[184:185], 0, s[96:97]
	v_lshl_add_u64 v[200:201], v[186:187], 0, s[96:97]
	s_waitcnt vmcnt(8) lgkmcnt(3)
	v_mfma_f32_16x16x32_bf16 v[16:19], v[128:131], v[236:239], v[16:19]
	v_mfma_f32_16x16x32_bf16 v[24:27], v[132:135], v[236:239], v[24:27]
	v_mfma_f32_16x16x32_bf16 v[0:3], v[136:139], v[236:239], v[0:3]
	v_mfma_f32_16x16x32_bf16 v[8:11], v[140:143], v[236:239], v[8:11]
	ds_read_b128 v[236:239], v196 offset:4096
	s_waitcnt lgkmcnt(3)
	v_mfma_f32_16x16x32_bf16 v[20:23], v[128:131], v[240:243], v[20:23]
	v_mfma_f32_16x16x32_bf16 v[28:31], v[132:135], v[240:243], v[28:31]
	v_mfma_f32_16x16x32_bf16 v[4:7], v[136:139], v[240:243], v[4:7]
	v_mfma_f32_16x16x32_bf16 v[12:15], v[140:143], v[240:243], v[12:15]
	ds_read_b128 v[240:243], v196 offset:5120
	s_waitcnt lgkmcnt(3)
	v_mfma_f32_16x16x32_bf16 v[112:115], v[128:131], v[244:247], v[112:115]
	v_mfma_f32_16x16x32_bf16 v[120:123], v[132:135], v[244:247], v[120:123]
	v_mfma_f32_16x16x32_bf16 v[96:99], v[136:139], v[244:247], v[96:99]
	v_mfma_f32_16x16x32_bf16 v[104:107], v[140:143], v[244:247], v[104:107]
	ds_read_b128 v[244:247], v196 offset:6144
	s_waitcnt lgkmcnt(3)
	v_mfma_f32_16x16x32_bf16 v[116:119], v[128:131], v[248:251], v[116:119]
	v_mfma_f32_16x16x32_bf16 v[124:127], v[132:135], v[248:251], v[124:127]
	v_mfma_f32_16x16x32_bf16 v[100:103], v[136:139], v[248:251], v[100:103]
	v_mfma_f32_16x16x32_bf16 v[108:111], v[140:143], v[248:251], v[108:111]
	ds_read_b128 v[248:251], v196 offset:7168
	s_waitcnt lgkmcnt(3)
	v_mfma_f32_16x16x32_bf16 v[80:83], v[128:131], v[236:239], v[80:83]
	v_mfma_f32_16x16x32_bf16 v[88:91], v[132:135], v[236:239], v[88:91]
	v_mfma_f32_16x16x32_bf16 v[48:51], v[136:139], v[236:239], v[48:51]
	v_mfma_f32_16x16x32_bf16 v[56:59], v[140:143], v[236:239], v[56:59]
	s_waitcnt lgkmcnt(2)
	v_mfma_f32_16x16x32_bf16 v[84:87], v[128:131], v[240:243], v[84:87]
	v_mfma_f32_16x16x32_bf16 v[92:95], v[132:135], v[240:243], v[92:95]
	v_mfma_f32_16x16x32_bf16 v[52:55], v[136:139], v[240:243], v[52:55]
	v_mfma_f32_16x16x32_bf16 v[60:63], v[140:143], v[240:243], v[60:63]
	s_waitcnt lgkmcnt(1)
	v_mfma_f32_16x16x32_bf16 v[64:67], v[128:131], v[244:247], v[64:67]
	v_mfma_f32_16x16x32_bf16 v[72:75], v[132:135], v[244:247], v[72:75]
	v_mfma_f32_16x16x32_bf16 v[32:35], v[136:139], v[244:247], v[32:35]
	v_mfma_f32_16x16x32_bf16 v[40:43], v[140:143], v[244:247], v[40:43]
	s_waitcnt lgkmcnt(0)
	v_mfma_f32_16x16x32_bf16 v[68:71], v[128:131], v[248:251], v[68:71]
	v_mfma_f32_16x16x32_bf16 v[76:79], v[132:135], v[248:251], v[76:79]
	v_mfma_f32_16x16x32_bf16 v[36:39], v[136:139], v[248:251], v[36:39]
	v_mfma_f32_16x16x32_bf16 v[44:47], v[140:143], v[248:251], v[44:47]
	global_load_dwordx4 v[128:131], v[198:199], off
	global_load_dwordx4 v[132:135], v[198:199], off offset:256
	global_load_dwordx4 v[136:139], v[200:201], off
	global_load_dwordx4 v[140:143], v[200:201], off offset:256
	s_waitcnt vmcnt(10)
	s_barrier
	s_add_i32 s3, s1, 3
	s_lshl_b32 s96, s3, 13
	s_mov_b32 m0, vcc_lo
	v_lshl_add_u64 v[160:161], v[188:189], 0, s[96:97]
	global_load_lds_dwordx4 v[160:161], off
	global_load_lds_dwordx4 v[160:161], off offset:1024
	ds_read_b128 v[236:239], v196 offset:8192
	ds_read_b128 v[240:243], v196 offset:9216
	ds_read_b128 v[244:247], v196 offset:10240
	ds_read_b128 v[248:251], v196 offset:11264
	s_add_i32 s3, s1, 3
	s_lshl_b32 s96, s3, 11
	v_lshl_add_u64 v[198:199], v[184:185], 0, s[96:97]
	v_lshl_add_u64 v[200:201], v[186:187], 0, s[96:97]
	s_waitcnt vmcnt(8) lgkmcnt(3)
	v_mfma_f32_16x16x32_bf16 v[16:19], v[144:147], v[236:239], v[16:19]
	v_mfma_f32_16x16x32_bf16 v[24:27], v[148:151], v[236:239], v[24:27]
	v_mfma_f32_16x16x32_bf16 v[0:3], v[152:155], v[236:239], v[0:3]
	v_mfma_f32_16x16x32_bf16 v[8:11], v[156:159], v[236:239], v[8:11]
	ds_read_b128 v[236:239], v196 offset:12288
	s_waitcnt lgkmcnt(3)
	v_mfma_f32_16x16x32_bf16 v[20:23], v[144:147], v[240:243], v[20:23]
	v_mfma_f32_16x16x32_bf16 v[28:31], v[148:151], v[240:243], v[28:31]
	v_mfma_f32_16x16x32_bf16 v[4:7], v[152:155], v[240:243], v[4:7]
	v_mfma_f32_16x16x32_bf16 v[12:15], v[156:159], v[240:243], v[12:15]
	ds_read_b128 v[240:243], v196 offset:13312
	s_waitcnt lgkmcnt(3)
	v_mfma_f32_16x16x32_bf16 v[112:115], v[144:147], v[244:247], v[112:115]
	v_mfma_f32_16x16x32_bf16 v[120:123], v[148:151], v[244:247], v[120:123]
	v_mfma_f32_16x16x32_bf16 v[96:99], v[152:155], v[244:247], v[96:99]
	v_mfma_f32_16x16x32_bf16 v[104:107], v[156:159], v[244:247], v[104:107]
	ds_read_b128 v[244:247], v196 offset:14336
	s_waitcnt lgkmcnt(3)
	v_mfma_f32_16x16x32_bf16 v[116:119], v[144:147], v[248:251], v[116:119]
	v_mfma_f32_16x16x32_bf16 v[124:127], v[148:151], v[248:251], v[124:127]
	v_mfma_f32_16x16x32_bf16 v[100:103], v[152:155], v[248:251], v[100:103]
	v_mfma_f32_16x16x32_bf16 v[108:111], v[156:159], v[248:251], v[108:111]
	ds_read_b128 v[248:251], v196 offset:15360
	s_waitcnt lgkmcnt(3)
	v_mfma_f32_16x16x32_bf16 v[80:83], v[144:147], v[236:239], v[80:83]
	v_mfma_f32_16x16x32_bf16 v[88:91], v[148:151], v[236:239], v[88:91]
	v_mfma_f32_16x16x32_bf16 v[48:51], v[152:155], v[236:239], v[48:51]
	v_mfma_f32_16x16x32_bf16 v[56:59], v[156:159], v[236:239], v[56:59]
	s_waitcnt lgkmcnt(2)
	v_mfma_f32_16x16x32_bf16 v[84:87], v[144:147], v[240:243], v[84:87]
	v_mfma_f32_16x16x32_bf16 v[92:95], v[148:151], v[240:243], v[92:95]
	v_mfma_f32_16x16x32_bf16 v[52:55], v[152:155], v[240:243], v[52:55]
	v_mfma_f32_16x16x32_bf16 v[60:63], v[156:159], v[240:243], v[60:63]
	s_waitcnt lgkmcnt(1)
	v_mfma_f32_16x16x32_bf16 v[64:67], v[144:147], v[244:247], v[64:67]
	v_mfma_f32_16x16x32_bf16 v[72:75], v[148:151], v[244:247], v[72:75]
	v_mfma_f32_16x16x32_bf16 v[32:35], v[152:155], v[244:247], v[32:35]
	v_mfma_f32_16x16x32_bf16 v[40:43], v[156:159], v[244:247], v[40:43]
	s_waitcnt lgkmcnt(0)
	v_mfma_f32_16x16x32_bf16 v[68:71], v[144:147], v[248:251], v[68:71]
	v_mfma_f32_16x16x32_bf16 v[76:79], v[148:151], v[248:251], v[76:79]
	v_mfma_f32_16x16x32_bf16 v[36:39], v[152:155], v[248:251], v[36:39]
	v_mfma_f32_16x16x32_bf16 v[44:47], v[156:159], v[248:251], v[44:47]
	global_load_dwordx4 v[144:147], v[198:199], off
	global_load_dwordx4 v[148:151], v[198:199], off offset:256
	global_load_dwordx4 v[152:155], v[200:201], off
	global_load_dwordx4 v[156:159], v[200:201], off offset:256
	s_waitcnt vmcnt(10)
	s_barrier
	s_add_i32 s3, s1, 4
	s_lshl_b32 s96, s3, 13
	s_add_i32 m0, vcc_lo, 8192
	v_lshl_add_u64 v[160:161], v[188:189], 0, s[96:97]
	global_load_lds_dwordx4 v[160:161], off
	global_load_lds_dwordx4 v[160:161], off offset:1024
	ds_read_b128 v[236:239], v196 offset:16384
	ds_read_b128 v[240:243], v196 offset:17408
	ds_read_b128 v[244:247], v196 offset:18432
	ds_read_b128 v[248:251], v196 offset:19456
	s_add_i32 s3, s1, 4
	s_lshl_b32 s96, s3, 11
	v_lshl_add_u64 v[198:199], v[184:185], 0, s[96:97]
	v_lshl_add_u64 v[200:201], v[186:187], 0, s[96:97]
	s_waitcnt vmcnt(8) lgkmcnt(3)
	v_mfma_f32_16x16x32_bf16 v[16:19], v[128:131], v[236:239], v[16:19]
	v_mfma_f32_16x16x32_bf16 v[24:27], v[132:135], v[236:239], v[24:27]
	v_mfma_f32_16x16x32_bf16 v[0:3], v[136:139], v[236:239], v[0:3]
	v_mfma_f32_16x16x32_bf16 v[8:11], v[140:143], v[236:239], v[8:11]
	ds_read_b128 v[236:239], v196 offset:20480
	s_waitcnt lgkmcnt(3)
	v_mfma_f32_16x16x32_bf16 v[20:23], v[128:131], v[240:243], v[20:23]
	v_mfma_f32_16x16x32_bf16 v[28:31], v[132:135], v[240:243], v[28:31]
	v_mfma_f32_16x16x32_bf16 v[4:7], v[136:139], v[240:243], v[4:7]
	v_mfma_f32_16x16x32_bf16 v[12:15], v[140:143], v[240:243], v[12:15]
	ds_read_b128 v[240:243], v196 offset:21504
	s_waitcnt lgkmcnt(3)
	v_mfma_f32_16x16x32_bf16 v[112:115], v[128:131], v[244:247], v[112:115]
	v_mfma_f32_16x16x32_bf16 v[120:123], v[132:135], v[244:247], v[120:123]
	v_mfma_f32_16x16x32_bf16 v[96:99], v[136:139], v[244:247], v[96:99]
	v_mfma_f32_16x16x32_bf16 v[104:107], v[140:143], v[244:247], v[104:107]
	ds_read_b128 v[244:247], v196 offset:22528
	s_waitcnt lgkmcnt(3)
	v_mfma_f32_16x16x32_bf16 v[116:119], v[128:131], v[248:251], v[116:119]
	v_mfma_f32_16x16x32_bf16 v[124:127], v[132:135], v[248:251], v[124:127]
	v_mfma_f32_16x16x32_bf16 v[100:103], v[136:139], v[248:251], v[100:103]
	v_mfma_f32_16x16x32_bf16 v[108:111], v[140:143], v[248:251], v[108:111]
	ds_read_b128 v[248:251], v196 offset:23552
	s_waitcnt lgkmcnt(3)
	v_mfma_f32_16x16x32_bf16 v[80:83], v[128:131], v[236:239], v[80:83]
	v_mfma_f32_16x16x32_bf16 v[88:91], v[132:135], v[236:239], v[88:91]
	v_mfma_f32_16x16x32_bf16 v[48:51], v[136:139], v[236:239], v[48:51]
	v_mfma_f32_16x16x32_bf16 v[56:59], v[140:143], v[236:239], v[56:59]
	s_waitcnt lgkmcnt(2)
	v_mfma_f32_16x16x32_bf16 v[84:87], v[128:131], v[240:243], v[84:87]
	v_mfma_f32_16x16x32_bf16 v[92:95], v[132:135], v[240:243], v[92:95]
	v_mfma_f32_16x16x32_bf16 v[52:55], v[136:139], v[240:243], v[52:55]
	v_mfma_f32_16x16x32_bf16 v[60:63], v[140:143], v[240:243], v[60:63]
	s_waitcnt lgkmcnt(1)
	v_mfma_f32_16x16x32_bf16 v[64:67], v[128:131], v[244:247], v[64:67]
	v_mfma_f32_16x16x32_bf16 v[72:75], v[132:135], v[244:247], v[72:75]
	v_mfma_f32_16x16x32_bf16 v[32:35], v[136:139], v[244:247], v[32:35]
	v_mfma_f32_16x16x32_bf16 v[40:43], v[140:143], v[244:247], v[40:43]
	s_waitcnt lgkmcnt(0)
	v_mfma_f32_16x16x32_bf16 v[68:71], v[128:131], v[248:251], v[68:71]
	v_mfma_f32_16x16x32_bf16 v[76:79], v[132:135], v[248:251], v[76:79]
	v_mfma_f32_16x16x32_bf16 v[36:39], v[136:139], v[248:251], v[36:39]
	v_mfma_f32_16x16x32_bf16 v[44:47], v[140:143], v[248:251], v[44:47]
	global_load_dwordx4 v[128:131], v[198:199], off
	global_load_dwordx4 v[132:135], v[198:199], off offset:256
	global_load_dwordx4 v[136:139], v[200:201], off
	global_load_dwordx4 v[140:143], v[200:201], off offset:256
	s_waitcnt vmcnt(10)
	s_barrier
	s_add_i32 s3, s1, 5
	s_lshl_b32 s96, s3, 13
	s_add_i32 m0, vcc_lo, 16384
	v_lshl_add_u64 v[160:161], v[188:189], 0, s[96:97]
	global_load_lds_dwordx4 v[160:161], off
	global_load_lds_dwordx4 v[160:161], off offset:1024
	ds_read_b128 v[236:239], v196 offset:0
	ds_read_b128 v[240:243], v196 offset:1024
	ds_read_b128 v[244:247], v196 offset:2048
	ds_read_b128 v[248:251], v196 offset:3072
	s_add_i32 s3, s1, 5
	s_lshl_b32 s96, s3, 11
	v_lshl_add_u64 v[198:199], v[184:185], 0, s[96:97]
	v_lshl_add_u64 v[200:201], v[186:187], 0, s[96:97]
	s_waitcnt vmcnt(8) lgkmcnt(3)
	v_mfma_f32_16x16x32_bf16 v[16:19], v[144:147], v[236:239], v[16:19]
	v_mfma_f32_16x16x32_bf16 v[24:27], v[148:151], v[236:239], v[24:27]
	v_mfma_f32_16x16x32_bf16 v[0:3], v[152:155], v[236:239], v[0:3]
	v_mfma_f32_16x16x32_bf16 v[8:11], v[156:159], v[236:239], v[8:11]
	ds_read_b128 v[236:239], v196 offset:4096
	s_waitcnt lgkmcnt(3)
	v_mfma_f32_16x16x32_bf16 v[20:23], v[144:147], v[240:243], v[20:23]
	v_mfma_f32_16x16x32_bf16 v[28:31], v[148:151], v[240:243], v[28:31]
	v_mfma_f32_16x16x32_bf16 v[4:7], v[152:155], v[240:243], v[4:7]
	v_mfma_f32_16x16x32_bf16 v[12:15], v[156:159], v[240:243], v[12:15]
	ds_read_b128 v[240:243], v196 offset:5120
	s_waitcnt lgkmcnt(3)
	v_mfma_f32_16x16x32_bf16 v[112:115], v[144:147], v[244:247], v[112:115]
	v_mfma_f32_16x16x32_bf16 v[120:123], v[148:151], v[244:247], v[120:123]
	v_mfma_f32_16x16x32_bf16 v[96:99], v[152:155], v[244:247], v[96:99]
	v_mfma_f32_16x16x32_bf16 v[104:107], v[156:159], v[244:247], v[104:107]
	ds_read_b128 v[244:247], v196 offset:6144
	s_waitcnt lgkmcnt(3)
	v_mfma_f32_16x16x32_bf16 v[116:119], v[144:147], v[248:251], v[116:119]
	v_mfma_f32_16x16x32_bf16 v[124:127], v[148:151], v[248:251], v[124:127]
	v_mfma_f32_16x16x32_bf16 v[100:103], v[152:155], v[248:251], v[100:103]
	v_mfma_f32_16x16x32_bf16 v[108:111], v[156:159], v[248:251], v[108:111]
	ds_read_b128 v[248:251], v196 offset:7168
	s_waitcnt lgkmcnt(3)
	v_mfma_f32_16x16x32_bf16 v[80:83], v[144:147], v[236:239], v[80:83]
	v_mfma_f32_16x16x32_bf16 v[88:91], v[148:151], v[236:239], v[88:91]
	v_mfma_f32_16x16x32_bf16 v[48:51], v[152:155], v[236:239], v[48:51]
	v_mfma_f32_16x16x32_bf16 v[56:59], v[156:159], v[236:239], v[56:59]
	s_waitcnt lgkmcnt(2)
	v_mfma_f32_16x16x32_bf16 v[84:87], v[144:147], v[240:243], v[84:87]
	v_mfma_f32_16x16x32_bf16 v[92:95], v[148:151], v[240:243], v[92:95]
	v_mfma_f32_16x16x32_bf16 v[52:55], v[152:155], v[240:243], v[52:55]
	v_mfma_f32_16x16x32_bf16 v[60:63], v[156:159], v[240:243], v[60:63]
	s_waitcnt lgkmcnt(1)
	v_mfma_f32_16x16x32_bf16 v[64:67], v[144:147], v[244:247], v[64:67]
	v_mfma_f32_16x16x32_bf16 v[72:75], v[148:151], v[244:247], v[72:75]
	v_mfma_f32_16x16x32_bf16 v[32:35], v[152:155], v[244:247], v[32:35]
	v_mfma_f32_16x16x32_bf16 v[40:43], v[156:159], v[244:247], v[40:43]
	s_waitcnt lgkmcnt(0)
	v_mfma_f32_16x16x32_bf16 v[68:71], v[144:147], v[248:251], v[68:71]
	v_mfma_f32_16x16x32_bf16 v[76:79], v[148:151], v[248:251], v[76:79]
	v_mfma_f32_16x16x32_bf16 v[36:39], v[152:155], v[248:251], v[36:39]
	v_mfma_f32_16x16x32_bf16 v[44:47], v[156:159], v[248:251], v[44:47]
	global_load_dwordx4 v[144:147], v[198:199], off
	global_load_dwordx4 v[148:151], v[198:199], off offset:256
	global_load_dwordx4 v[152:155], v[200:201], off
	global_load_dwordx4 v[156:159], v[200:201], off offset:256
	s_waitcnt vmcnt(10)
	s_barrier
	s_add_i32 s3, s1, 6
	s_lshl_b32 s96, s3, 13
	s_mov_b32 m0, vcc_lo
	v_lshl_add_u64 v[160:161], v[188:189], 0, s[96:97]
	global_load_lds_dwordx4 v[160:161], off
	global_load_lds_dwordx4 v[160:161], off offset:1024
	ds_read_b128 v[236:239], v196 offset:8192
	ds_read_b128 v[240:243], v196 offset:9216
	ds_read_b128 v[244:247], v196 offset:10240
	ds_read_b128 v[248:251], v196 offset:11264
	s_add_i32 s3, s1, 6
	s_lshl_b32 s96, s3, 11
	v_lshl_add_u64 v[198:199], v[184:185], 0, s[96:97]
	v_lshl_add_u64 v[200:201], v[186:187], 0, s[96:97]
	s_waitcnt vmcnt(8) lgkmcnt(3)
	v_mfma_f32_16x16x32_bf16 v[16:19], v[128:131], v[236:239], v[16:19]
	v_mfma_f32_16x16x32_bf16 v[24:27], v[132:135], v[236:239], v[24:27]
	v_mfma_f32_16x16x32_bf16 v[0:3], v[136:139], v[236:239], v[0:3]
	v_mfma_f32_16x16x32_bf16 v[8:11], v[140:143], v[236:239], v[8:11]
	ds_read_b128 v[236:239], v196 offset:12288
	s_waitcnt lgkmcnt(3)
	v_mfma_f32_16x16x32_bf16 v[20:23], v[128:131], v[240:243], v[20:23]
	v_mfma_f32_16x16x32_bf16 v[28:31], v[132:135], v[240:243], v[28:31]
	v_mfma_f32_16x16x32_bf16 v[4:7], v[136:139], v[240:243], v[4:7]
	v_mfma_f32_16x16x32_bf16 v[12:15], v[140:143], v[240:243], v[12:15]
	ds_read_b128 v[240:243], v196 offset:13312
	s_waitcnt lgkmcnt(3)
	v_mfma_f32_16x16x32_bf16 v[112:115], v[128:131], v[244:247], v[112:115]
	v_mfma_f32_16x16x32_bf16 v[120:123], v[132:135], v[244:247], v[120:123]
	v_mfma_f32_16x16x32_bf16 v[96:99], v[136:139], v[244:247], v[96:99]
	v_mfma_f32_16x16x32_bf16 v[104:107], v[140:143], v[244:247], v[104:107]
	ds_read_b128 v[244:247], v196 offset:14336
	s_waitcnt lgkmcnt(3)
	v_mfma_f32_16x16x32_bf16 v[116:119], v[128:131], v[248:251], v[116:119]
	v_mfma_f32_16x16x32_bf16 v[124:127], v[132:135], v[248:251], v[124:127]
	v_mfma_f32_16x16x32_bf16 v[100:103], v[136:139], v[248:251], v[100:103]
	v_mfma_f32_16x16x32_bf16 v[108:111], v[140:143], v[248:251], v[108:111]
	ds_read_b128 v[248:251], v196 offset:15360
	s_waitcnt lgkmcnt(3)
	v_mfma_f32_16x16x32_bf16 v[80:83], v[128:131], v[236:239], v[80:83]
	v_mfma_f32_16x16x32_bf16 v[88:91], v[132:135], v[236:239], v[88:91]
	v_mfma_f32_16x16x32_bf16 v[48:51], v[136:139], v[236:239], v[48:51]
	v_mfma_f32_16x16x32_bf16 v[56:59], v[140:143], v[236:239], v[56:59]
	s_waitcnt lgkmcnt(2)
	v_mfma_f32_16x16x32_bf16 v[84:87], v[128:131], v[240:243], v[84:87]
	v_mfma_f32_16x16x32_bf16 v[92:95], v[132:135], v[240:243], v[92:95]
	v_mfma_f32_16x16x32_bf16 v[52:55], v[136:139], v[240:243], v[52:55]
	v_mfma_f32_16x16x32_bf16 v[60:63], v[140:143], v[240:243], v[60:63]
	s_waitcnt lgkmcnt(1)
	v_mfma_f32_16x16x32_bf16 v[64:67], v[128:131], v[244:247], v[64:67]
	v_mfma_f32_16x16x32_bf16 v[72:75], v[132:135], v[244:247], v[72:75]
	v_mfma_f32_16x16x32_bf16 v[32:35], v[136:139], v[244:247], v[32:35]
	v_mfma_f32_16x16x32_bf16 v[40:43], v[140:143], v[244:247], v[40:43]
	s_waitcnt lgkmcnt(0)
	v_mfma_f32_16x16x32_bf16 v[68:71], v[128:131], v[248:251], v[68:71]
	v_mfma_f32_16x16x32_bf16 v[76:79], v[132:135], v[248:251], v[76:79]
	v_mfma_f32_16x16x32_bf16 v[36:39], v[136:139], v[248:251], v[36:39]
	v_mfma_f32_16x16x32_bf16 v[44:47], v[140:143], v[248:251], v[44:47]
	global_load_dwordx4 v[128:131], v[198:199], off
	global_load_dwordx4 v[132:135], v[198:199], off offset:256
	global_load_dwordx4 v[136:139], v[200:201], off
	global_load_dwordx4 v[140:143], v[200:201], off offset:256
	s_waitcnt vmcnt(10)
	s_barrier
	s_add_i32 s3, s1, 7
	s_lshl_b32 s96, s3, 13
	s_add_i32 m0, vcc_lo, 8192
	v_lshl_add_u64 v[160:161], v[188:189], 0, s[96:97]
	global_load_lds_dwordx4 v[160:161], off
	global_load_lds_dwordx4 v[160:161], off offset:1024
	ds_read_b128 v[236:239], v196 offset:16384
	ds_read_b128 v[240:243], v196 offset:17408
	ds_read_b128 v[244:247], v196 offset:18432
	ds_read_b128 v[248:251], v196 offset:19456
	s_add_i32 s3, s1, 7
	s_lshl_b32 s96, s3, 11
	v_lshl_add_u64 v[198:199], v[184:185], 0, s[96:97]
	v_lshl_add_u64 v[200:201], v[186:187], 0, s[96:97]
	s_waitcnt vmcnt(8) lgkmcnt(3)
	v_mfma_f32_16x16x32_bf16 v[16:19], v[144:147], v[236:239], v[16:19]
	v_mfma_f32_16x16x32_bf16 v[24:27], v[148:151], v[236:239], v[24:27]
	v_mfma_f32_16x16x32_bf16 v[0:3], v[152:155], v[236:239], v[0:3]
	v_mfma_f32_16x16x32_bf16 v[8:11], v[156:159], v[236:239], v[8:11]
	ds_read_b128 v[236:239], v196 offset:20480
	s_waitcnt lgkmcnt(3)
	v_mfma_f32_16x16x32_bf16 v[20:23], v[144:147], v[240:243], v[20:23]
	v_mfma_f32_16x16x32_bf16 v[28:31], v[148:151], v[240:243], v[28:31]
	v_mfma_f32_16x16x32_bf16 v[4:7], v[152:155], v[240:243], v[4:7]
	v_mfma_f32_16x16x32_bf16 v[12:15], v[156:159], v[240:243], v[12:15]
	ds_read_b128 v[240:243], v196 offset:21504
	s_waitcnt lgkmcnt(3)
	v_mfma_f32_16x16x32_bf16 v[112:115], v[144:147], v[244:247], v[112:115]
	v_mfma_f32_16x16x32_bf16 v[120:123], v[148:151], v[244:247], v[120:123]
	v_mfma_f32_16x16x32_bf16 v[96:99], v[152:155], v[244:247], v[96:99]
	v_mfma_f32_16x16x32_bf16 v[104:107], v[156:159], v[244:247], v[104:107]
	ds_read_b128 v[244:247], v196 offset:22528
	s_waitcnt lgkmcnt(3)
	v_mfma_f32_16x16x32_bf16 v[116:119], v[144:147], v[248:251], v[116:119]
	v_mfma_f32_16x16x32_bf16 v[124:127], v[148:151], v[248:251], v[124:127]
	v_mfma_f32_16x16x32_bf16 v[100:103], v[152:155], v[248:251], v[100:103]
	v_mfma_f32_16x16x32_bf16 v[108:111], v[156:159], v[248:251], v[108:111]
	ds_read_b128 v[248:251], v196 offset:23552
	s_waitcnt lgkmcnt(3)
	v_mfma_f32_16x16x32_bf16 v[80:83], v[144:147], v[236:239], v[80:83]
	v_mfma_f32_16x16x32_bf16 v[88:91], v[148:151], v[236:239], v[88:91]
	v_mfma_f32_16x16x32_bf16 v[48:51], v[152:155], v[236:239], v[48:51]
	v_mfma_f32_16x16x32_bf16 v[56:59], v[156:159], v[236:239], v[56:59]
	s_waitcnt lgkmcnt(2)
	v_mfma_f32_16x16x32_bf16 v[84:87], v[144:147], v[240:243], v[84:87]
	v_mfma_f32_16x16x32_bf16 v[92:95], v[148:151], v[240:243], v[92:95]
	v_mfma_f32_16x16x32_bf16 v[52:55], v[152:155], v[240:243], v[52:55]
	v_mfma_f32_16x16x32_bf16 v[60:63], v[156:159], v[240:243], v[60:63]
	s_waitcnt lgkmcnt(1)
	v_mfma_f32_16x16x32_bf16 v[64:67], v[144:147], v[244:247], v[64:67]
	v_mfma_f32_16x16x32_bf16 v[72:75], v[148:151], v[244:247], v[72:75]
	v_mfma_f32_16x16x32_bf16 v[32:35], v[152:155], v[244:247], v[32:35]
	v_mfma_f32_16x16x32_bf16 v[40:43], v[156:159], v[244:247], v[40:43]
	s_waitcnt lgkmcnt(0)
	v_mfma_f32_16x16x32_bf16 v[68:71], v[144:147], v[248:251], v[68:71]
	v_mfma_f32_16x16x32_bf16 v[76:79], v[148:151], v[248:251], v[76:79]
	v_mfma_f32_16x16x32_bf16 v[36:39], v[152:155], v[248:251], v[36:39]
	v_mfma_f32_16x16x32_bf16 v[44:47], v[156:159], v[248:251], v[44:47]
	global_load_dwordx4 v[144:147], v[198:199], off
	global_load_dwordx4 v[148:151], v[198:199], off offset:256
	global_load_dwordx4 v[152:155], v[200:201], off
	global_load_dwordx4 v[156:159], v[200:201], off offset:256
	s_waitcnt vmcnt(10)
	s_barrier
	s_add_i32 s1, s1, 6
	s_cmp_lt_u32 s1, 30
	s_cbranch_scc1 .Lg16_proj_k
	ds_read_b128 v[236:239], v196 offset:0
	ds_read_b128 v[240:243], v196 offset:1024
	ds_read_b128 v[244:247], v196 offset:2048
	ds_read_b128 v[248:251], v196 offset:3072
	s_waitcnt vmcnt(6) lgkmcnt(3)
	v_mfma_f32_16x16x32_bf16 v[16:19], v[128:131], v[236:239], v[16:19]
	v_mfma_f32_16x16x32_bf16 v[24:27], v[132:135], v[236:239], v[24:27]
	v_mfma_f32_16x16x32_bf16 v[0:3], v[136:139], v[236:239], v[0:3]
	v_mfma_f32_16x16x32_bf16 v[8:11], v[140:143], v[236:239], v[8:11]
	ds_read_b128 v[236:239], v196 offset:4096
	s_waitcnt lgkmcnt(3)
	v_mfma_f32_16x16x32_bf16 v[20:23], v[128:131], v[240:243], v[20:23]
	v_mfma_f32_16x16x32_bf16 v[28:31], v[132:135], v[240:243], v[28:31]
	v_mfma_f32_16x16x32_bf16 v[4:7], v[136:139], v[240:243], v[4:7]
	v_mfma_f32_16x16x32_bf16 v[12:15], v[140:143], v[240:243], v[12:15]
	ds_read_b128 v[240:243], v196 offset:5120
	s_waitcnt lgkmcnt(3)
	v_mfma_f32_16x16x32_bf16 v[112:115], v[128:131], v[244:247], v[112:115]
	v_mfma_f32_16x16x32_bf16 v[120:123], v[132:135], v[244:247], v[120:123]
	v_mfma_f32_16x16x32_bf16 v[96:99], v[136:139], v[244:247], v[96:99]
	v_mfma_f32_16x16x32_bf16 v[104:107], v[140:143], v[244:247], v[104:107]
	ds_read_b128 v[244:247], v196 offset:6144
	s_waitcnt lgkmcnt(3)
	v_mfma_f32_16x16x32_bf16 v[116:119], v[128:131], v[248:251], v[116:119]
	v_mfma_f32_16x16x32_bf16 v[124:127], v[132:135], v[248:251], v[124:127]
	v_mfma_f32_16x16x32_bf16 v[100:103], v[136:139], v[248:251], v[100:103]
	v_mfma_f32_16x16x32_bf16 v[108:111], v[140:143], v[248:251], v[108:111]
	ds_read_b128 v[248:251], v196 offset:7168
	s_waitcnt lgkmcnt(3)
	v_mfma_f32_16x16x32_bf16 v[80:83], v[128:131], v[236:239], v[80:83]
	v_mfma_f32_16x16x32_bf16 v[88:91], v[132:135], v[236:239], v[88:91]
	v_mfma_f32_16x16x32_bf16 v[48:51], v[136:139], v[236:239], v[48:51]
	v_mfma_f32_16x16x32_bf16 v[56:59], v[140:143], v[236:239], v[56:59]
	s_waitcnt lgkmcnt(2)
	v_mfma_f32_16x16x32_bf16 v[84:87], v[128:131], v[240:243], v[84:87]
	v_mfma_f32_16x16x32_bf16 v[92:95], v[132:135], v[240:243], v[92:95]
	v_mfma_f32_16x16x32_bf16 v[52:55], v[136:139], v[240:243], v[52:55]
	v_mfma_f32_16x16x32_bf16 v[60:63], v[140:143], v[240:243], v[60:63]
	s_waitcnt lgkmcnt(1)
	v_mfma_f32_16x16x32_bf16 v[64:67], v[128:131], v[244:247], v[64:67]
	v_mfma_f32_16x16x32_bf16 v[72:75], v[132:135], v[244:247], v[72:75]
	v_mfma_f32_16x16x32_bf16 v[32:35], v[136:139], v[244:247], v[32:35]
	v_mfma_f32_16x16x32_bf16 v[40:43], v[140:143], v[244:247], v[40:43]
	s_waitcnt lgkmcnt(0)
	v_mfma_f32_16x16x32_bf16 v[68:71], v[128:131], v[248:251], v[68:71]
	v_mfma_f32_16x16x32_bf16 v[76:79], v[132:135], v[248:251], v[76:79]
	v_mfma_f32_16x16x32_bf16 v[36:39], v[136:139], v[248:251], v[36:39]
	v_mfma_f32_16x16x32_bf16 v[44:47], v[140:143], v[248:251], v[44:47]
	s_waitcnt vmcnt(4)
	s_barrier
	ds_read_b128 v[236:239], v196 offset:8192
	ds_read_b128 v[240:243], v196 offset:9216
	ds_read_b128 v[244:247], v196 offset:10240
	ds_read_b128 v[248:251], v196 offset:11264
	s_waitcnt vmcnt(0) lgkmcnt(3)
	v_mfma_f32_16x16x32_bf16 v[16:19], v[144:147], v[236:239], v[16:19]
	v_mfma_f32_16x16x32_bf16 v[24:27], v[148:151], v[236:239], v[24:27]
	v_mfma_f32_16x16x32_bf16 v[0:3], v[152:155], v[236:239], v[0:3]
	v_mfma_f32_16x16x32_bf16 v[8:11], v[156:159], v[236:239], v[8:11]
	ds_read_b128 v[236:239], v196 offset:12288
	s_waitcnt lgkmcnt(3)
	v_mfma_f32_16x16x32_bf16 v[20:23], v[144:147], v[240:243], v[20:23]
	v_mfma_f32_16x16x32_bf16 v[28:31], v[148:151], v[240:243], v[28:31]
	v_mfma_f32_16x16x32_bf16 v[4:7], v[152:155], v[240:243], v[4:7]
	v_mfma_f32_16x16x32_bf16 v[12:15], v[156:159], v[240:243], v[12:15]
	ds_read_b128 v[240:243], v196 offset:13312
	s_waitcnt lgkmcnt(3)
	v_mfma_f32_16x16x32_bf16 v[112:115], v[144:147], v[244:247], v[112:115]
	v_mfma_f32_16x16x32_bf16 v[120:123], v[148:151], v[244:247], v[120:123]
	v_mfma_f32_16x16x32_bf16 v[96:99], v[152:155], v[244:247], v[96:99]
	v_mfma_f32_16x16x32_bf16 v[104:107], v[156:159], v[244:247], v[104:107]
	ds_read_b128 v[244:247], v196 offset:14336
	s_waitcnt lgkmcnt(3)
	v_mfma_f32_16x16x32_bf16 v[116:119], v[144:147], v[248:251], v[116:119]
	v_mfma_f32_16x16x32_bf16 v[124:127], v[148:151], v[248:251], v[124:127]
	v_mfma_f32_16x16x32_bf16 v[100:103], v[152:155], v[248:251], v[100:103]
	v_mfma_f32_16x16x32_bf16 v[108:111], v[156:159], v[248:251], v[108:111]
	ds_read_b128 v[248:251], v196 offset:15360
	v_permlane16_swap_b32_e32 v16, v20
	v_permlane16_swap_b32_e32 v17, v21
	v_permlane16_swap_b32_e32 v18, v22
	v_permlane16_swap_b32_e32 v19, v23
	v_permlane16_swap_b32_e32 v24, v28
	v_permlane16_swap_b32_e32 v25, v29
	v_permlane16_swap_b32_e32 v26, v30
	v_permlane16_swap_b32_e32 v27, v31
	v_permlane16_swap_b32_e32 v0, v4
	v_permlane16_swap_b32_e32 v1, v5
	v_permlane16_swap_b32_e32 v2, v6
	v_permlane16_swap_b32_e32 v3, v7
	v_permlane16_swap_b32_e32 v8, v12
	v_permlane16_swap_b32_e32 v9, v13
	v_permlane16_swap_b32_e32 v10, v14
	v_permlane16_swap_b32_e32 v11, v15
	v_permlane32_swap_b32_e32 v16, v20
	v_permlane32_swap_b32_e32 v17, v21
	v_permlane32_swap_b32_e32 v18, v22
	v_permlane32_swap_b32_e32 v19, v23
	v_permlane32_swap_b32_e32 v24, v28
	v_permlane32_swap_b32_e32 v25, v29
	v_permlane32_swap_b32_e32 v26, v30
	v_permlane32_swap_b32_e32 v27, v31
	v_permlane32_swap_b32_e32 v0, v4
	v_permlane32_swap_b32_e32 v1, v5
	v_permlane32_swap_b32_e32 v2, v6
	v_permlane32_swap_b32_e32 v3, v7
	v_permlane32_swap_b32_e32 v8, v12
	v_permlane32_swap_b32_e32 v9, v13
	v_permlane32_swap_b32_e32 v10, v14
	v_permlane32_swap_b32_e32 v11, v15
	s_waitcnt lgkmcnt(3)
	v_mfma_f32_16x16x32_bf16 v[80:83], v[144:147], v[236:239], v[80:83]
	v_mfma_f32_16x16x32_bf16 v[88:91], v[148:151], v[236:239], v[88:91]
	v_mfma_f32_16x16x32_bf16 v[48:51], v[152:155], v[236:239], v[48:51]
	v_mfma_f32_16x16x32_bf16 v[56:59], v[156:159], v[236:239], v[56:59]
	s_waitcnt lgkmcnt(2)
	v_mfma_f32_16x16x32_bf16 v[84:87], v[144:147], v[240:243], v[84:87]
	v_mfma_f32_16x16x32_bf16 v[92:95], v[148:151], v[240:243], v[92:95]
	v_mfma_f32_16x16x32_bf16 v[52:55], v[152:155], v[240:243], v[52:55]
	v_mfma_f32_16x16x32_bf16 v[60:63], v[156:159], v[240:243], v[60:63]
	v_permlane16_swap_b32_e32 v112, v116
	v_permlane16_swap_b32_e32 v113, v117
	v_permlane16_swap_b32_e32 v114, v118
	v_permlane16_swap_b32_e32 v115, v119
	v_permlane16_swap_b32_e32 v120, v124
	v_permlane16_swap_b32_e32 v121, v125
	v_permlane16_swap_b32_e32 v122, v126
	v_permlane16_swap_b32_e32 v123, v127
	v_permlane16_swap_b32_e32 v96, v100
	v_permlane16_swap_b32_e32 v97, v101
	v_permlane16_swap_b32_e32 v98, v102
	v_permlane16_swap_b32_e32 v99, v103
	v_permlane16_swap_b32_e32 v104, v108
	v_permlane16_swap_b32_e32 v105, v109
	v_permlane16_swap_b32_e32 v106, v110
	v_permlane16_swap_b32_e32 v107, v111
	v_permlane32_swap_b32_e32 v112, v116
	v_permlane32_swap_b32_e32 v113, v117
	v_permlane32_swap_b32_e32 v114, v118
	v_permlane32_swap_b32_e32 v115, v119
	v_permlane32_swap_b32_e32 v120, v124
	v_permlane32_swap_b32_e32 v121, v125
	v_permlane32_swap_b32_e32 v122, v126
	v_permlane32_swap_b32_e32 v123, v127
	v_permlane32_swap_b32_e32 v96, v100
	v_permlane32_swap_b32_e32 v97, v101
	v_permlane32_swap_b32_e32 v98, v102
	v_permlane32_swap_b32_e32 v99, v103
	v_permlane32_swap_b32_e32 v104, v108
	v_permlane32_swap_b32_e32 v105, v109
	v_permlane32_swap_b32_e32 v106, v110
	v_permlane32_swap_b32_e32 v107, v111
	s_waitcnt lgkmcnt(1)
	v_mfma_f32_16x16x32_bf16 v[64:67], v[144:147], v[244:247], v[64:67]
	v_mfma_f32_16x16x32_bf16 v[72:75], v[148:151], v[244:247], v[72:75]
	v_mfma_f32_16x16x32_bf16 v[32:35], v[152:155], v[244:247], v[32:35]
	v_mfma_f32_16x16x32_bf16 v[40:43], v[156:159], v[244:247], v[40:43]
	s_waitcnt lgkmcnt(0)
	v_mfma_f32_16x16x32_bf16 v[68:71], v[144:147], v[248:251], v[68:71]
	v_mfma_f32_16x16x32_bf16 v[76:79], v[148:151], v[248:251], v[76:79]
	v_mfma_f32_16x16x32_bf16 v[36:39], v[152:155], v[248:251], v[36:39]
	v_mfma_f32_16x16x32_bf16 v[44:47], v[156:159], v[248:251], v[44:47]
	v_permlane16_swap_b32_e32 v80, v84
	v_permlane16_swap_b32_e32 v81, v85
	v_permlane16_swap_b32_e32 v82, v86
	v_permlane16_swap_b32_e32 v83, v87
	v_permlane16_swap_b32_e32 v88, v92
	v_permlane16_swap_b32_e32 v89, v93
	v_permlane16_swap_b32_e32 v90, v94
	v_permlane16_swap_b32_e32 v91, v95
	v_permlane16_swap_b32_e32 v48, v52
	v_permlane16_swap_b32_e32 v49, v53
	v_permlane16_swap_b32_e32 v50, v54
	v_permlane16_swap_b32_e32 v51, v55
	v_permlane16_swap_b32_e32 v56, v60
	v_permlane16_swap_b32_e32 v57, v61
	v_permlane16_swap_b32_e32 v58, v62
	v_permlane16_swap_b32_e32 v59, v63
	v_permlane32_swap_b32_e32 v80, v84
	v_permlane32_swap_b32_e32 v81, v85
	v_permlane32_swap_b32_e32 v82, v86
	v_permlane32_swap_b32_e32 v83, v87
	v_permlane32_swap_b32_e32 v88, v92
	v_permlane32_swap_b32_e32 v89, v93
	v_permlane32_swap_b32_e32 v90, v94
	v_permlane32_swap_b32_e32 v91, v95
	v_permlane32_swap_b32_e32 v48, v52
	v_permlane32_swap_b32_e32 v49, v53
	v_permlane32_swap_b32_e32 v50, v54
	v_permlane32_swap_b32_e32 v51, v55
	v_permlane32_swap_b32_e32 v56, v60
	v_permlane32_swap_b32_e32 v57, v61
	v_permlane32_swap_b32_e32 v58, v62
	v_permlane32_swap_b32_e32 v59, v63
	s_barrier
	s_nop 7
	v_permlane16_swap_b32_e32 v64, v68
	v_permlane16_swap_b32_e32 v65, v69
	v_permlane16_swap_b32_e32 v66, v70
	v_permlane16_swap_b32_e32 v67, v71
	v_permlane16_swap_b32_e32 v72, v76
	v_permlane16_swap_b32_e32 v73, v77
	v_permlane16_swap_b32_e32 v74, v78
	v_permlane16_swap_b32_e32 v75, v79
	v_permlane16_swap_b32_e32 v32, v36
	v_permlane16_swap_b32_e32 v33, v37
	v_permlane16_swap_b32_e32 v34, v38
	v_permlane16_swap_b32_e32 v35, v39
	v_permlane16_swap_b32_e32 v40, v44
	v_permlane16_swap_b32_e32 v41, v45
	v_permlane16_swap_b32_e32 v42, v46
	v_permlane16_swap_b32_e32 v43, v47
	v_permlane32_swap_b32_e32 v64, v68
	v_permlane32_swap_b32_e32 v65, v69
	v_permlane32_swap_b32_e32 v66, v70
	v_permlane32_swap_b32_e32 v67, v71
	v_permlane32_swap_b32_e32 v72, v76
	v_permlane32_swap_b32_e32 v73, v77
	v_permlane32_swap_b32_e32 v74, v78
	v_permlane32_swap_b32_e32 v75, v79
	v_permlane32_swap_b32_e32 v32, v36
	v_permlane32_swap_b32_e32 v33, v37
	v_permlane32_swap_b32_e32 v34, v38
	v_permlane32_swap_b32_e32 v35, v39
	v_permlane32_swap_b32_e32 v40, v44
	v_permlane32_swap_b32_e32 v41, v45
	v_permlane32_swap_b32_e32 v42, v46
	v_permlane32_swap_b32_e32 v43, v47
	s_waitcnt vmcnt(0)
	s_waitcnt vmcnt(0)
	v_and_b32_e32 v128, 63, v179
	v_lshrrev_b32_e32 v129, 6, v179
	s_lshl_b32 s20, s2, 8
	s_cmp_eq_u32 s0, 23
	s_cbranch_scc1 .Lpe_proj_ab
	v_readlane_b32 s14, v254, 15
	v_readlane_b32 s15, v254, 16
	v_readlane_b32 s16, v254, 17
	v_readlane_b32 s17, v254, 18
	s_movk_i32 s22, 0x900
	s_movk_i32 s23, 0x300
	s_cmp_lt_u32 s0, 20
	s_cselect_b32 s14, s14, s16
	s_cselect_b32 s15, s15, s17
	s_cselect_b32 s18, s22, s23
	s_movk_i32 s22, 0xf500
	s_movk_i32 s23, 0xec00
	s_cselect_b32 s19, s22, s23
	s_movk_i32 s22, 0xb00
	s_cmp_lt_u32 s0, 11
	s_cselect_b32 s14, s66, s14
	s_cselect_b32 s15, s67, s15
	s_cselect_b32 s18, s22, s18
	s_cselect_b32 s19, 0, s19
	s_mul_hi_u32 s21, s20, s18
	s_mul_i32 s20, s20, s18
	s_lshl_b32 s22, s0, 8
	s_add_i32 s22, s22, s19
	s_add_u32 s12, s14, s20
	s_addc_u32 s13, s15, s21
	s_add_u32 s12, s12, s22
	s_addc_u32 s13, s13, 0
	v_mul_u32_u24_e32 v188, 0x2400, v129
	v_lshrrev_b32_e32 v189, 5, v128
	v_mul_u32_u24_e32 v189, 0x240, v189
	v_add_u32_e32 v130, v188, v189
	v_and_b32_e32 v189, 31, v128
	v_lshl_add_u32 v130, v189, 1, v130
	v_lshrrev_b32_e32 v189, 3, v128
	v_mul_u32_u24_e32 v132, 0x90, v189
	v_add_u32_e32 v131, v188, v132
	v_and_b32_e32 v188, 7, v128
	v_lshlrev_b32_e32 v188, 4, v188
	v_add_u32_e32 v131, v131, v188
	v_lshl_add_u32 v189, v129, 6, v189
	v_add_u32_e32 v132, 0, v189
	v_add_u32_e32 v133, 8, v189
	v_add_u32_e32 v134, 16, v189
	v_add_u32_e32 v135, 24, v189
	v_add_u32_e32 v136, 32, v189
	v_add_u32_e32 v137, 40, v189
	v_add_u32_e32 v138, 48, v189
	v_add_u32_e32 v139, 56, v189
	v_mul_lo_u32 v132, v132, s18
	v_mul_lo_u32 v133, v133, s18
	v_mul_lo_u32 v134, v134, s18
	v_mul_lo_u32 v135, v135, s18
	v_mul_lo_u32 v136, v136, s18
	v_mul_lo_u32 v137, v137, s18
	v_mul_lo_u32 v138, v138, s18
	v_mul_lo_u32 v139, v139, s18
	v_add_u32_e32 v132, v132, v188
	v_add_u32_e32 v133, v133, v188
	v_add_u32_e32 v134, v134, v188
	v_add_u32_e32 v135, v135, v188
	v_add_u32_e32 v136, v136, v188
	v_add_u32_e32 v137, v137, v188
	v_add_u32_e32 v138, v138, v188
	v_add_u32_e32 v139, v139, v188
	v_cvt_pk_bf16_f32 v140, v16, v16
	v_cvt_pk_bf16_f32 v141, v112, v112
	v_cvt_pk_bf16_f32 v142, v17, v17
	v_cvt_pk_bf16_f32 v143, v113, v113
	v_cvt_pk_bf16_f32 v144, v18, v18
	v_cvt_pk_bf16_f32 v145, v114, v114
	v_cvt_pk_bf16_f32 v146, v19, v19
	v_cvt_pk_bf16_f32 v147, v115, v115
	ds_write_b16 v130, v140
	ds_write_b16 v130, v141 offset:64
	ds_write_b16 v130, v142 offset:144
	ds_write_b16 v130, v143 offset:208
	ds_write_b16 v130, v144 offset:288
	ds_write_b16 v130, v145 offset:352
	ds_write_b16 v130, v146 offset:432
	ds_write_b16 v130, v147 offset:496
	v_cvt_pk_bf16_f32 v140, v20, v20
	v_cvt_pk_bf16_f32 v141, v116, v116
	v_cvt_pk_bf16_f32 v142, v21, v21
	v_cvt_pk_bf16_f32 v143, v117, v117
	v_cvt_pk_bf16_f32 v144, v22, v22
	v_cvt_pk_bf16_f32 v145, v118, v118
	v_cvt_pk_bf16_f32 v146, v23, v23
	v_cvt_pk_bf16_f32 v147, v119, v119
	ds_write_b16 v130, v140 offset:1152
	ds_write_b16 v130, v141 offset:1216
	ds_write_b16 v130, v142 offset:1296
	ds_write_b16 v130, v143 offset:1360
	ds_write_b16 v130, v144 offset:1440
	ds_write_b16 v130, v145 offset:1504
	ds_write_b16 v130, v146 offset:1584
	ds_write_b16 v130, v147 offset:1648
	v_cvt_pk_bf16_f32 v140, v24, v24
	v_cvt_pk_bf16_f32 v141, v120, v120
	v_cvt_pk_bf16_f32 v142, v25, v25
	v_cvt_pk_bf16_f32 v143, v121, v121
	v_cvt_pk_bf16_f32 v144, v26, v26
	v_cvt_pk_bf16_f32 v145, v122, v122
	v_cvt_pk_bf16_f32 v146, v27, v27
	v_cvt_pk_bf16_f32 v147, v123, v123
	ds_write_b16 v130, v140 offset:2304
	ds_write_b16 v130, v141 offset:2368
	ds_write_b16 v130, v142 offset:2448
	ds_write_b16 v130, v143 offset:2512
	ds_write_b16 v130, v144 offset:2592
	ds_write_b16 v130, v145 offset:2656
	ds_write_b16 v130, v146 offset:2736
	ds_write_b16 v130, v147 offset:2800
	v_cvt_pk_bf16_f32 v140, v28, v28
	v_cvt_pk_bf16_f32 v141, v124, v124
	v_cvt_pk_bf16_f32 v142, v29, v29
	v_cvt_pk_bf16_f32 v143, v125, v125
	v_cvt_pk_bf16_f32 v144, v30, v30
	v_cvt_pk_bf16_f32 v145, v126, v126
	v_cvt_pk_bf16_f32 v146, v31, v31
	v_cvt_pk_bf16_f32 v147, v127, v127
	ds_write_b16 v130, v140 offset:3456
	ds_write_b16 v130, v141 offset:3520
	ds_write_b16 v130, v142 offset:3600
	ds_write_b16 v130, v143 offset:3664
	ds_write_b16 v130, v144 offset:3744
	ds_write_b16 v130, v145 offset:3808
	ds_write_b16 v130, v146 offset:3888
	ds_write_b16 v130, v147 offset:3952
	v_cvt_pk_bf16_f32 v140, v0, v0
	v_cvt_pk_bf16_f32 v141, v96, v96
	v_cvt_pk_bf16_f32 v142, v1, v1
	v_cvt_pk_bf16_f32 v143, v97, v97
	v_cvt_pk_bf16_f32 v144, v2, v2
	v_cvt_pk_bf16_f32 v145, v98, v98
	v_cvt_pk_bf16_f32 v146, v3, v3
	v_cvt_pk_bf16_f32 v147, v99, v99
	ds_write_b16 v130, v140 offset:4608
	ds_write_b16 v130, v141 offset:4672
	ds_write_b16 v130, v142 offset:4752
	ds_write_b16 v130, v143 offset:4816
	ds_write_b16 v130, v144 offset:4896
	ds_write_b16 v130, v145 offset:4960
	ds_write_b16 v130, v146 offset:5040
	ds_write_b16 v130, v147 offset:5104
	v_cvt_pk_bf16_f32 v140, v4, v4
	v_cvt_pk_bf16_f32 v141, v100, v100
	v_cvt_pk_bf16_f32 v142, v5, v5
	v_cvt_pk_bf16_f32 v143, v101, v101
	v_cvt_pk_bf16_f32 v144, v6, v6
	v_cvt_pk_bf16_f32 v145, v102, v102
	v_cvt_pk_bf16_f32 v146, v7, v7
	v_cvt_pk_bf16_f32 v147, v103, v103
	ds_write_b16 v130, v140 offset:5760
	ds_write_b16 v130, v141 offset:5824
	ds_write_b16 v130, v142 offset:5904
	ds_write_b16 v130, v143 offset:5968
	ds_write_b16 v130, v144 offset:6048
	ds_write_b16 v130, v145 offset:6112
	ds_write_b16 v130, v146 offset:6192
	ds_write_b16 v130, v147 offset:6256
	v_cvt_pk_bf16_f32 v140, v8, v8
	v_cvt_pk_bf16_f32 v141, v104, v104
	v_cvt_pk_bf16_f32 v142, v9, v9
	v_cvt_pk_bf16_f32 v143, v105, v105
	v_cvt_pk_bf16_f32 v144, v10, v10
	v_cvt_pk_bf16_f32 v145, v106, v106
	v_cvt_pk_bf16_f32 v146, v11, v11
	v_cvt_pk_bf16_f32 v147, v107, v107
	ds_write_b16 v130, v140 offset:6912
	ds_write_b16 v130, v141 offset:6976
	ds_write_b16 v130, v142 offset:7056
	ds_write_b16 v130, v143 offset:7120
	ds_write_b16 v130, v144 offset:7200
	ds_write_b16 v130, v145 offset:7264
	ds_write_b16 v130, v146 offset:7344
	ds_write_b16 v130, v147 offset:7408
	v_cvt_pk_bf16_f32 v140, v12, v12
	v_cvt_pk_bf16_f32 v141, v108, v108
	v_cvt_pk_bf16_f32 v142, v13, v13
	v_cvt_pk_bf16_f32 v143, v109, v109
	v_cvt_pk_bf16_f32 v144, v14, v14
	v_cvt_pk_bf16_f32 v145, v110, v110
	v_cvt_pk_bf16_f32 v146, v15, v15
	v_cvt_pk_bf16_f32 v147, v111, v111
	ds_write_b16 v130, v140 offset:8064
	ds_write_b16 v130, v141 offset:8128
	ds_write_b16 v130, v142 offset:8208
	ds_write_b16 v130, v143 offset:8272
	ds_write_b16 v130, v144 offset:8352
	ds_write_b16 v130, v145 offset:8416
	ds_write_b16 v130, v146 offset:8496
	ds_write_b16 v130, v147 offset:8560
	s_waitcnt lgkmcnt(0)
	ds_read_b128 v[148:151], v131
	ds_read_b128 v[152:155], v131 offset:1152
	ds_read_b128 v[156:159], v131 offset:2304
	ds_read_b128 v[160:163], v131 offset:3456
	ds_read_b128 v[164:167], v131 offset:4608
	ds_read_b128 v[168:171], v131 offset:5760
	ds_read_b128 v[172:175], v131 offset:6912
	ds_read_b128 v[184:187], v131 offset:8064
	s_waitcnt lgkmcnt(7)
	global_store_dwordx4 v132, v[148:151], s[12:13]
	s_waitcnt lgkmcnt(6)
	global_store_dwordx4 v133, v[152:155], s[12:13]
	s_waitcnt lgkmcnt(5)
	global_store_dwordx4 v134, v[156:159], s[12:13]
	s_waitcnt lgkmcnt(4)
	global_store_dwordx4 v135, v[160:163], s[12:13]
	s_waitcnt lgkmcnt(3)
	global_store_dwordx4 v136, v[164:167], s[12:13]
	s_waitcnt lgkmcnt(2)
	global_store_dwordx4 v137, v[168:171], s[12:13]
	s_waitcnt lgkmcnt(1)
	global_store_dwordx4 v138, v[172:175], s[12:13]
	s_waitcnt lgkmcnt(0)
	global_store_dwordx4 v139, v[184:187], s[12:13]
	v_cvt_pk_bf16_f32 v140, v80, v80
	v_cvt_pk_bf16_f32 v141, v64, v64
	v_cvt_pk_bf16_f32 v142, v81, v81
	v_cvt_pk_bf16_f32 v143, v65, v65
	v_cvt_pk_bf16_f32 v144, v82, v82
	v_cvt_pk_bf16_f32 v145, v66, v66
	v_cvt_pk_bf16_f32 v146, v83, v83
	v_cvt_pk_bf16_f32 v147, v67, v67
	ds_write_b16 v130, v140
	ds_write_b16 v130, v141 offset:64
	ds_write_b16 v130, v142 offset:144
	ds_write_b16 v130, v143 offset:208
	ds_write_b16 v130, v144 offset:288
	ds_write_b16 v130, v145 offset:352
	ds_write_b16 v130, v146 offset:432
	ds_write_b16 v130, v147 offset:496
	v_cvt_pk_bf16_f32 v140, v84, v84
	v_cvt_pk_bf16_f32 v141, v68, v68
	v_cvt_pk_bf16_f32 v142, v85, v85
	v_cvt_pk_bf16_f32 v143, v69, v69
	v_cvt_pk_bf16_f32 v144, v86, v86
	v_cvt_pk_bf16_f32 v145, v70, v70
	v_cvt_pk_bf16_f32 v146, v87, v87
	v_cvt_pk_bf16_f32 v147, v71, v71
	ds_write_b16 v130, v140 offset:1152
	ds_write_b16 v130, v141 offset:1216
	ds_write_b16 v130, v142 offset:1296
	ds_write_b16 v130, v143 offset:1360
	ds_write_b16 v130, v144 offset:1440
	ds_write_b16 v130, v145 offset:1504
	ds_write_b16 v130, v146 offset:1584
	ds_write_b16 v130, v147 offset:1648
	v_cvt_pk_bf16_f32 v140, v88, v88
	v_cvt_pk_bf16_f32 v141, v72, v72
	v_cvt_pk_bf16_f32 v142, v89, v89
	v_cvt_pk_bf16_f32 v143, v73, v73
	v_cvt_pk_bf16_f32 v144, v90, v90
	v_cvt_pk_bf16_f32 v145, v74, v74
	v_cvt_pk_bf16_f32 v146, v91, v91
	v_cvt_pk_bf16_f32 v147, v75, v75
	ds_write_b16 v130, v140 offset:2304
	ds_write_b16 v130, v141 offset:2368
	ds_write_b16 v130, v142 offset:2448
	ds_write_b16 v130, v143 offset:2512
	ds_write_b16 v130, v144 offset:2592
	ds_write_b16 v130, v145 offset:2656
	ds_write_b16 v130, v146 offset:2736
	ds_write_b16 v130, v147 offset:2800
	v_cvt_pk_bf16_f32 v140, v92, v92
	v_cvt_pk_bf16_f32 v141, v76, v76
	v_cvt_pk_bf16_f32 v142, v93, v93
	v_cvt_pk_bf16_f32 v143, v77, v77
	v_cvt_pk_bf16_f32 v144, v94, v94
	v_cvt_pk_bf16_f32 v145, v78, v78
	v_cvt_pk_bf16_f32 v146, v95, v95
	v_cvt_pk_bf16_f32 v147, v79, v79
	ds_write_b16 v130, v140 offset:3456
	ds_write_b16 v130, v141 offset:3520
	ds_write_b16 v130, v142 offset:3600
	ds_write_b16 v130, v143 offset:3664
	ds_write_b16 v130, v144 offset:3744
	ds_write_b16 v130, v145 offset:3808
	ds_write_b16 v130, v146 offset:3888
	ds_write_b16 v130, v147 offset:3952
	v_cvt_pk_bf16_f32 v140, v48, v48
	v_cvt_pk_bf16_f32 v141, v32, v32
	v_cvt_pk_bf16_f32 v142, v49, v49
	v_cvt_pk_bf16_f32 v143, v33, v33
	v_cvt_pk_bf16_f32 v144, v50, v50
	v_cvt_pk_bf16_f32 v145, v34, v34
	v_cvt_pk_bf16_f32 v146, v51, v51
	v_cvt_pk_bf16_f32 v147, v35, v35
	ds_write_b16 v130, v140 offset:4608
	ds_write_b16 v130, v141 offset:4672
	ds_write_b16 v130, v142 offset:4752
	ds_write_b16 v130, v143 offset:4816
	ds_write_b16 v130, v144 offset:4896
	ds_write_b16 v130, v145 offset:4960
	ds_write_b16 v130, v146 offset:5040
	ds_write_b16 v130, v147 offset:5104
	v_cvt_pk_bf16_f32 v140, v52, v52
	v_cvt_pk_bf16_f32 v141, v36, v36
	v_cvt_pk_bf16_f32 v142, v53, v53
	v_cvt_pk_bf16_f32 v143, v37, v37
	v_cvt_pk_bf16_f32 v144, v54, v54
	v_cvt_pk_bf16_f32 v145, v38, v38
	v_cvt_pk_bf16_f32 v146, v55, v55
	v_cvt_pk_bf16_f32 v147, v39, v39
	ds_write_b16 v130, v140 offset:5760
	ds_write_b16 v130, v141 offset:5824
	ds_write_b16 v130, v142 offset:5904
	ds_write_b16 v130, v143 offset:5968
	ds_write_b16 v130, v144 offset:6048
	ds_write_b16 v130, v145 offset:6112
	ds_write_b16 v130, v146 offset:6192
	ds_write_b16 v130, v147 offset:6256
	v_cvt_pk_bf16_f32 v140, v56, v56
	v_cvt_pk_bf16_f32 v141, v40, v40
	v_cvt_pk_bf16_f32 v142, v57, v57
	v_cvt_pk_bf16_f32 v143, v41, v41
	v_cvt_pk_bf16_f32 v144, v58, v58
	v_cvt_pk_bf16_f32 v145, v42, v42
	v_cvt_pk_bf16_f32 v146, v59, v59
	v_cvt_pk_bf16_f32 v147, v43, v43
	ds_write_b16 v130, v140 offset:6912
	ds_write_b16 v130, v141 offset:6976
	ds_write_b16 v130, v142 offset:7056
	ds_write_b16 v130, v143 offset:7120
	ds_write_b16 v130, v144 offset:7200
	ds_write_b16 v130, v145 offset:7264
	ds_write_b16 v130, v146 offset:7344
	ds_write_b16 v130, v147 offset:7408
	v_cvt_pk_bf16_f32 v140, v60, v60
	v_cvt_pk_bf16_f32 v141, v44, v44
	v_cvt_pk_bf16_f32 v142, v61, v61
	v_cvt_pk_bf16_f32 v143, v45, v45
	v_cvt_pk_bf16_f32 v144, v62, v62
	v_cvt_pk_bf16_f32 v145, v46, v46
	v_cvt_pk_bf16_f32 v146, v63, v63
	v_cvt_pk_bf16_f32 v147, v47, v47
	ds_write_b16 v130, v140 offset:8064
	ds_write_b16 v130, v141 offset:8128
	ds_write_b16 v130, v142 offset:8208
	ds_write_b16 v130, v143 offset:8272
	ds_write_b16 v130, v144 offset:8352
	ds_write_b16 v130, v145 offset:8416
	ds_write_b16 v130, v146 offset:8496
	ds_write_b16 v130, v147 offset:8560
	s_waitcnt lgkmcnt(0)
	ds_read_b128 v[148:151], v131
	ds_read_b128 v[152:155], v131 offset:1152
	ds_read_b128 v[156:159], v131 offset:2304
	ds_read_b128 v[160:163], v131 offset:3456
	ds_read_b128 v[164:167], v131 offset:4608
	ds_read_b128 v[168:171], v131 offset:5760
	ds_read_b128 v[172:175], v131 offset:6912
	ds_read_b128 v[184:187], v131 offset:8064
	s_waitcnt lgkmcnt(7)
	global_store_dwordx4 v132, v[148:151], s[12:13] offset:128
	s_waitcnt lgkmcnt(6)
	global_store_dwordx4 v133, v[152:155], s[12:13] offset:128
	s_waitcnt lgkmcnt(5)
	global_store_dwordx4 v134, v[156:159], s[12:13] offset:128
	s_waitcnt lgkmcnt(4)
	global_store_dwordx4 v135, v[160:163], s[12:13] offset:128
	s_waitcnt lgkmcnt(3)
	global_store_dwordx4 v136, v[164:167], s[12:13] offset:128
	s_waitcnt lgkmcnt(2)
	global_store_dwordx4 v137, v[168:171], s[12:13] offset:128
	s_waitcnt lgkmcnt(1)
	global_store_dwordx4 v138, v[172:175], s[12:13] offset:128
	s_waitcnt lgkmcnt(0)
	global_store_dwordx4 v139, v[184:187], s[12:13] offset:128
	s_branch .Lpe_proj_end
.Lpe_proj_ab:
	v_readlane_b32 s14, v254, 19
	v_readlane_b32 s15, v254, 20
	s_mul_i32 s20, s20, 0x60
	s_add_u32 s12, s14, s20
	s_addc_u32 s13, s15, 0
	v_lshrrev_b32_e32 v189, 5, v128
	v_lshlrev_b32_e32 v189, 2, v189
	v_lshl_add_u32 v189, v129, 6, v189
	v_mul_u32_u24_e32 v189, 0x60, v189
	v_and_b32_e32 v188, 31, v128
	v_lshl_add_u32 v189, v188, 2, v189
	v_cmp_gt_u32_e32 vcc, 24, v188
	s_and_saveexec_b64 s[14:15], vcc
	global_store_dword v189, v16, s[12:13]
	global_store_dword v189, v17, s[12:13] offset:96
	global_store_dword v189, v18, s[12:13] offset:192
	global_store_dword v189, v19, s[12:13] offset:288
	global_store_dword v189, v20, s[12:13] offset:768
	global_store_dword v189, v21, s[12:13] offset:864
	global_store_dword v189, v22, s[12:13] offset:960
	global_store_dword v189, v23, s[12:13] offset:1056
	global_store_dword v189, v24, s[12:13] offset:1536
	global_store_dword v189, v25, s[12:13] offset:1632
	global_store_dword v189, v26, s[12:13] offset:1728
	global_store_dword v189, v27, s[12:13] offset:1824
	global_store_dword v189, v28, s[12:13] offset:2304
	global_store_dword v189, v29, s[12:13] offset:2400
	global_store_dword v189, v30, s[12:13] offset:2496
	global_store_dword v189, v31, s[12:13] offset:2592
	s_add_u32 s12, s12, 0xc00
	s_addc_u32 s13, s13, 0
	global_store_dword v189, v0, s[12:13]
	global_store_dword v189, v1, s[12:13] offset:96
	global_store_dword v189, v2, s[12:13] offset:192
	global_store_dword v189, v3, s[12:13] offset:288
	global_store_dword v189, v4, s[12:13] offset:768
	global_store_dword v189, v5, s[12:13] offset:864
	global_store_dword v189, v6, s[12:13] offset:960
	global_store_dword v189, v7, s[12:13] offset:1056
	global_store_dword v189, v8, s[12:13] offset:1536
	global_store_dword v189, v9, s[12:13] offset:1632
	global_store_dword v189, v10, s[12:13] offset:1728
	global_store_dword v189, v11, s[12:13] offset:1824
	global_store_dword v189, v12, s[12:13] offset:2304
	global_store_dword v189, v13, s[12:13] offset:2400
	global_store_dword v189, v14, s[12:13] offset:2496
	global_store_dword v189, v15, s[12:13] offset:2592
	s_mov_b64 exec, s[14:15]
.Lpe_proj_end:
	v_readlane_b32 s16, v254, 11
	s_add_i32 s8, s8, s16
	s_cmpk_lt_i32 s8, 0x198
	s_barrier
	s_cbranch_scc1 .LBB0_215
	s_branch .LBB0_350
